# in-proj: MFMAs of the all-padding half (columns 4736..4863) of the last column tile skipped
# baseline (speedup 1.0000x reference)
; #define PG8_STAGE(bufoff, gbase, voff) do { _Pragma("unroll") for (int _i = 0; _i < 2; ++_i) \
;         __builtin_amdgcn_global_load_lds((const unsigned*)((const char*)(gbase) + (voff)[_i]), (PG8_LAS unsigned*)(lds + (bufoff) + ldsw + _i * 8192), 16, 0, 0); } while (0)
; #define PG8_LDA(dst, b, h) do { _Pragma("unroll") for (int m = 0; m < 4; ++m) _Pragma("unroll") for (int k = 0; k < 2; ++k) dst[m][k] = *(const PG8_LAS bf16x8*)(lds + PG8_SA(b, h) + aoff + m * 2048 + k * 1024); } while (0)
; #define PG8_LDB(dst, b, h) do { _Pragma("unroll") for (int n = 0; n < 2; ++n) _Pragma("unroll") for (int k = 0; k < 2; ++k) dst[n][k] = *(const PG8_LAS bf16x8*)(lds + PG8_SB(b, h) + boff + n * 2048 + k * 1024); } while (0)
; #define PG8_MMA(ai, bj, At, Bt) do { __builtin_amdgcn_s_setprio(1); _Pragma("unroll") for (int m = 0; m < 4; ++m) _Pragma("unroll") for (int n = 0; n < 2; ++n) _Pragma("unroll") for (int k = 0; k < 2; ++k) \
;         acc[ai][bj][m][n] = __builtin_amdgcn_mfma_f32_16x16x32_bf16(Bt[n][k], At[m][k], acc[ai][bj][m][n], 0, 0, 0); __builtin_amdgcn_s_setprio(0); } while (0)
; #define PG8_WAIT_V(n) asm volatile("s_waitcnt vmcnt(" #n ")" ::: "memory")
; #define PG8_WAIT_L(n) asm volatile("s_waitcnt lgkmcnt(" #n ")" ::: "memory")
; #define PG8_BAR __builtin_amdgcn_s_barrier()
; #define PG8_SCHED __builtin_amdgcn_sched_barrier(0)
; template <class Epi, class Sched, bool ALIGN_EPI = false, bool SP2 = false>
; __device__ __forceinline__ void gemm_phase(PG8_LAS unsigned char* lds, const Gemm g, const Sched& S, const Epi& E) {
;     ...
;             PG8_LDB(B0, 0, 0); PG8_LDB(B1, 0, 1); PG8_SCHED; PG8_LDA(At, 0, 0); PG8_STAGE(PG8_SA(1, 1), a1 + hstepA, voffA);
;             PG8_WAIT_V(8); PG8_WAIT_L(0); PG8_BAR; PG8_MMA(0, 0, At, B0); PG8_MMA(0, 1, At, B1); PG8_BAR; PG8_SCHED;
;             PG8_LDA(At, 0, 1); PG8_STAGE(PG8_SB(0, 0), b2, voffB); PG8_STAGE(PG8_SB(0, 1), b2 + hstepB, voffB); PG8_STAGE(PG8_SA(0, 0), a2, voffA);
;             PG8_WAIT_V(8); PG8_WAIT_L(0); PG8_BAR; PG8_MMA(1, 0, At, B0); PG8_MMA(1, 1, At, B1); PG8_BAR; PG8_SCHED;
.LBB0_1434:
	s_add_u32 s2, s6, 0xfff80080
	s_addc_u32 s33, s7, -1
	s_add_i32 s63, s17, 0x100
	s_cmp_eq_u32 s62, 28
	s_cselect_b32 s45, s35, s33
	s_cselect_b32 s44, s58, s2
	v_add_u32_e32 v146, s63, v149
	s_cselect_b32 s43, s27, s61
	s_cselect_b32 s42, s59, s60
	s_add_i32 s2, s24, 0x100
	ds_read_b128 v[142:145], v146
	ds_read_b128 v[154:157], v146 offset:1024
	ds_read_b128 v[158:161], v146 offset:2048
	ds_read_b128 v[162:165], v146 offset:3072
	v_add_u32_e32 v146, s2, v149
	ds_read_b128 v[166:169], v146
	ds_read_b128 v[170:173], v146 offset:1024
	ds_read_b128 v[174:177], v146 offset:2048
	ds_read_b128 v[178:181], v146 offset:3072
	v_lshl_add_u64 v[146:147], s[6:7], 0, v[138:139]
	s_add_i32 m0, s46, 0xc000
	ds_read_b128 v[182:185], v152
	ds_read_b128 v[186:189], v152 offset:1024
	ds_read_b128 v[190:193], v152 offset:2048
	ds_read_b128 v[210:213], v152 offset:3072
	ds_read_b128 v[228:231], v152 offset:4096
	ds_read_b128 v[232:235], v152 offset:5120
	ds_read_b128 v[236:239], v152 offset:6144
	ds_read_b128 v[240:243], v152 offset:7168
	global_load_lds_dwordx4 v[146:147], off
	v_lshl_add_u64 v[146:147], s[6:7], 0, v[140:141]
	s_add_i32 m0, s46, 0xe000
	s_nop 0
	global_load_lds_dwordx4 v[146:147], off
	s_waitcnt vmcnt(8)
	s_waitcnt lgkmcnt(0)
	s_barrier
	s_setprio 1
	s_waitcnt lgkmcnt(0)
	v_mfma_f32_16x16x32_bf16 v[126:129], v[142:145], v[182:185], v[126:129]
	v_mfma_f32_16x16x32_bf16 v[122:125], v[158:161], v[182:185], v[122:125]
	v_mfma_f32_16x16x32_bf16 v[110:113], v[142:145], v[190:193], v[110:113]
	v_mfma_f32_16x16x32_bf16 v[106:109], v[158:161], v[190:193], v[106:109]
	v_mfma_f32_16x16x32_bf16 v[94:97], v[142:145], v[228:231], v[94:97]
	v_mfma_f32_16x16x32_bf16 v[90:93], v[158:161], v[228:231], v[90:93]
	v_mfma_f32_16x16x32_bf16 v[78:81], v[142:145], v[236:239], v[78:81]
	v_mfma_f32_16x16x32_bf16 v[74:77], v[158:161], v[236:239], v[74:77]
	v_mfma_f32_16x16x32_bf16 v[126:129], v[154:157], v[186:189], v[126:129]
	v_mfma_f32_16x16x32_bf16 v[122:125], v[162:165], v[186:189], v[122:125]
	v_mfma_f32_16x16x32_bf16 v[110:113], v[154:157], v[210:213], v[110:113]
	v_mfma_f32_16x16x32_bf16 v[106:109], v[162:165], v[210:213], v[106:109]
	v_mfma_f32_16x16x32_bf16 v[94:97], v[154:157], v[232:235], v[94:97]
	v_mfma_f32_16x16x32_bf16 v[90:93], v[162:165], v[232:235], v[90:93]
	v_mfma_f32_16x16x32_bf16 v[78:81], v[154:157], v[240:243], v[78:81]
	v_mfma_f32_16x16x32_bf16 v[74:77], v[162:165], v[240:243], v[74:77]
	s_setprio 0
	s_cmp_eq_u32 s53, 18
	s_cbranch_scc1 .Linp_skip_0
	s_setprio 1
	v_mfma_f32_16x16x32_bf16 v[118:121], v[166:169], v[182:185], v[118:121]
	v_mfma_f32_16x16x32_bf16 v[114:117], v[174:177], v[182:185], v[114:117]
	v_mfma_f32_16x16x32_bf16 v[102:105], v[166:169], v[190:193], v[102:105]
	v_mfma_f32_16x16x32_bf16 v[98:101], v[174:177], v[190:193], v[98:101]
	v_mfma_f32_16x16x32_bf16 v[86:89], v[166:169], v[228:231], v[86:89]
	v_mfma_f32_16x16x32_bf16 v[82:85], v[174:177], v[228:231], v[82:85]
	v_mfma_f32_16x16x32_bf16 v[70:73], v[166:169], v[236:239], v[70:73]
	v_mfma_f32_16x16x32_bf16 v[66:69], v[174:177], v[236:239], v[66:69]
	v_mfma_f32_16x16x32_bf16 v[118:121], v[170:173], v[186:189], v[118:121]
	v_mfma_f32_16x16x32_bf16 v[114:117], v[178:181], v[186:189], v[114:117]
	v_mfma_f32_16x16x32_bf16 v[102:105], v[170:173], v[210:213], v[102:105]
	v_mfma_f32_16x16x32_bf16 v[98:101], v[178:181], v[210:213], v[98:101]
	v_mfma_f32_16x16x32_bf16 v[86:89], v[170:173], v[232:235], v[86:89]
	v_mfma_f32_16x16x32_bf16 v[82:85], v[178:181], v[232:235], v[82:85]
	v_mfma_f32_16x16x32_bf16 v[70:73], v[170:173], v[240:243], v[70:73]
	v_mfma_f32_16x16x32_bf16 v[66:69], v[178:181], v[240:243], v[66:69]
	s_setprio 0
.Linp_skip_0:
	s_barrier
	s_add_i32 s33, s63, s36
	v_lshl_add_u64 v[146:147], s[42:43], 0, v[0:1]
	s_mov_b32 m0, s33
	ds_read_b128 v[182:185], v152 offset:16384
	ds_read_b128 v[186:189], v152 offset:17408
	ds_read_b128 v[190:193], v152 offset:18432
	ds_read_b128 v[210:213], v152 offset:19456
	ds_read_b128 v[228:231], v152 offset:20480
	ds_read_b128 v[232:235], v152 offset:21504
	ds_read_b128 v[236:239], v152 offset:22528
	ds_read_b128 v[240:243], v152 offset:23552
	global_load_lds_dwordx4 v[146:147], off
	s_add_i32 m0, s33, 0x2000
	s_add_u32 s72, s42, 0x80000
	v_lshl_add_u64 v[194:195], s[42:43], 0, v[132:133]
	s_addc_u32 s73, s43, 0
	s_add_i32 s2, s2, s36
	global_load_lds_dwordx4 v[194:195], off
	v_lshl_add_u64 v[214:215], s[72:73], 0, v[0:1]
	s_mov_b32 m0, s2
	v_lshl_add_u64 v[222:223], s[44:45], 0, v[134:135]
	global_load_lds_dwordx4 v[214:215], off
	v_lshl_add_u64 v[214:215], s[72:73], 0, v[132:133]
	s_add_i32 m0, s2, 0x2000
	s_nop 0
	global_load_lds_dwordx4 v[214:215], off
	v_lshl_add_u64 v[214:215], s[44:45], 0, v[136:137]
	s_mov_b32 m0, s46
	s_nop 0
	global_load_lds_dwordx4 v[214:215], off
	s_mov_b32 m0, s47
	s_nop 0
	global_load_lds_dwordx4 v[222:223], off
	s_waitcnt vmcnt(8)
	s_waitcnt lgkmcnt(0)
	s_barrier
	s_setprio 1
	s_waitcnt lgkmcnt(0)
	v_mfma_f32_16x16x32_bf16 v[62:65], v[142:145], v[182:185], v[62:65]
	v_mfma_f32_16x16x32_bf16 v[58:61], v[158:161], v[182:185], v[58:61]
	v_mfma_f32_16x16x32_bf16 v[46:49], v[142:145], v[190:193], v[46:49]
	v_mfma_f32_16x16x32_bf16 v[42:45], v[158:161], v[190:193], v[42:45]
	v_mfma_f32_16x16x32_bf16 v[30:33], v[142:145], v[228:231], v[30:33]
	v_mfma_f32_16x16x32_bf16 v[26:29], v[158:161], v[228:231], v[26:29]
	v_mfma_f32_16x16x32_bf16 v[14:17], v[142:145], v[236:239], v[14:17]
	v_mfma_f32_16x16x32_bf16 v[10:13], v[158:161], v[236:239], v[10:13]
	v_mfma_f32_16x16x32_bf16 v[62:65], v[154:157], v[186:189], v[62:65]
	v_mfma_f32_16x16x32_bf16 v[58:61], v[162:165], v[186:189], v[58:61]
	v_mfma_f32_16x16x32_bf16 v[46:49], v[154:157], v[210:213], v[46:49]
	v_mfma_f32_16x16x32_bf16 v[42:45], v[162:165], v[210:213], v[42:45]
	v_mfma_f32_16x16x32_bf16 v[30:33], v[154:157], v[232:235], v[30:33]
	v_mfma_f32_16x16x32_bf16 v[26:29], v[162:165], v[232:235], v[26:29]
	v_mfma_f32_16x16x32_bf16 v[14:17], v[154:157], v[240:243], v[14:17]
	v_mfma_f32_16x16x32_bf16 v[10:13], v[162:165], v[240:243], v[10:13]
	s_setprio 0
	s_cmp_eq_u32 s53, 18
	s_cbranch_scc1 .Linp_skip_1
; #define PG8_STAGE(bufoff, gbase, voff) do { _Pragma("unroll") for (int _i = 0; _i < 2; ++_i) \
;         __builtin_amdgcn_global_load_lds((const unsigned*)((const char*)(gbase) + (voff)[_i]), (PG8_LAS unsigned*)(lds + (bufoff) + ldsw + _i * 8192), 16, 0, 0); } while (0)
; #define PG8_LDA(dst, b, h) do { _Pragma("unroll") for (int m = 0; m < 4; ++m) _Pragma("unroll") for (int k = 0; k < 2; ++k) dst[m][k] = *(const PG8_LAS bf16x8*)(lds + PG8_SA(b, h) + aoff + m * 2048 + k * 1024); } while (0)
; #define PG8_LDB(dst, b, h) do { _Pragma("unroll") for (int n = 0; n < 2; ++n) _Pragma("unroll") for (int k = 0; k < 2; ++k) dst[n][k] = *(const PG8_LAS bf16x8*)(lds + PG8_SB(b, h) + boff + n * 2048 + k * 1024); } while (0)
; #define PG8_MMA(ai, bj, At, Bt) do { __builtin_amdgcn_s_setprio(1); _Pragma("unroll") for (int m = 0; m < 4; ++m) _Pragma("unroll") for (int n = 0; n < 2; ++n) _Pragma("unroll") for (int k = 0; k < 2; ++k) \
;         acc[ai][bj][m][n] = __builtin_amdgcn_mfma_f32_16x16x32_bf16(Bt[n][k], At[m][k], acc[ai][bj][m][n], 0, 0, 0); __builtin_amdgcn_s_setprio(0); } while (0)
; #define PG8_WAIT_V(n) asm volatile("s_waitcnt vmcnt(" #n ")" ::: "memory")
; #define PG8_WAIT_L(n) asm volatile("s_waitcnt lgkmcnt(" #n ")" ::: "memory")
; #define PG8_BAR __builtin_amdgcn_s_barrier()
; #define PG8_SCHED __builtin_amdgcn_sched_barrier(0)
; template <class Epi, class Sched, bool ALIGN_EPI = false, bool SP2 = false>
; __device__ __forceinline__ void gemm_phase(PG8_LAS unsigned char* lds, const Gemm g, const Sched& S, const Epi& E) {
;     ...
;             PG8_WAIT_V(8); PG8_WAIT_L(0); PG8_BAR; PG8_MMA(1, 0, At, B0); PG8_MMA(1, 1, At, B1); PG8_BAR; PG8_SCHED;
;             PG8_LDB(B0, 1, 0); PG8_LDB(B1, 1, 1); PG8_SCHED; PG8_LDA(At, 1, 0); PG8_STAGE(PG8_SA(0, 1), a2 + hstepA, voffA);
;             PG8_WAIT_V(8); PG8_WAIT_L(0); PG8_BAR; PG8_MMA(0, 0, At, B0); PG8_MMA(0, 1, At, B1); PG8_BAR; PG8_SCHED;
	s_setprio 1
	v_mfma_f32_16x16x32_bf16 v[54:57], v[166:169], v[182:185], v[54:57]
	v_mfma_f32_16x16x32_bf16 v[50:53], v[174:177], v[182:185], v[50:53]
	v_mfma_f32_16x16x32_bf16 v[38:41], v[166:169], v[190:193], v[38:41]
	v_mfma_f32_16x16x32_bf16 v[34:37], v[174:177], v[190:193], v[34:37]
	v_mfma_f32_16x16x32_bf16 v[22:25], v[166:169], v[228:231], v[22:25]
	v_mfma_f32_16x16x32_bf16 v[18:21], v[174:177], v[228:231], v[18:21]
	v_mfma_f32_16x16x32_bf16 v[6:9], v[166:169], v[236:239], v[6:9]
	v_mfma_f32_16x16x32_bf16 v[2:5], v[174:177], v[236:239], v[2:5]
	v_mfma_f32_16x16x32_bf16 v[54:57], v[170:173], v[186:189], v[54:57]
	v_mfma_f32_16x16x32_bf16 v[50:53], v[178:181], v[186:189], v[50:53]
	v_mfma_f32_16x16x32_bf16 v[38:41], v[170:173], v[210:213], v[38:41]
	v_mfma_f32_16x16x32_bf16 v[34:37], v[178:181], v[210:213], v[34:37]
	v_mfma_f32_16x16x32_bf16 v[22:25], v[170:173], v[232:235], v[22:25]
	v_mfma_f32_16x16x32_bf16 v[18:21], v[178:181], v[232:235], v[18:21]
	v_mfma_f32_16x16x32_bf16 v[6:9], v[170:173], v[240:243], v[6:9]
	v_mfma_f32_16x16x32_bf16 v[2:5], v[178:181], v[240:243], v[2:5]
	s_setprio 0
.Linp_skip_1:
	s_barrier
	s_add_i32 s2, s87, 0x100
	v_add_u32_e32 v148, s2, v149
	s_add_i32 s33, s69, 0x100
	ds_read_b128 v[142:145], v148
	ds_read_b128 v[154:157], v148 offset:1024
	ds_read_b128 v[158:161], v148 offset:2048
	ds_read_b128 v[162:165], v148 offset:3072
	v_add_u32_e32 v148, s33, v149
	ds_read_b128 v[166:169], v148
	ds_read_b128 v[170:173], v148 offset:1024
	ds_read_b128 v[174:177], v148 offset:2048
	ds_read_b128 v[178:181], v148 offset:3072
	s_add_u32 s44, s44, 0x80000
	s_addc_u32 s45, s45, 0
	s_mov_b32 m0, s48
	v_lshl_add_u64 v[224:225], s[44:45], 0, v[136:137]
	ds_read_b128 v[182:185], v152 offset:32768
	ds_read_b128 v[186:189], v152 offset:33792
	ds_read_b128 v[190:193], v152 offset:34816
	ds_read_b128 v[210:213], v152 offset:35840
	ds_read_b128 v[228:231], v152 offset:36864
	ds_read_b128 v[232:235], v152 offset:37888
	ds_read_b128 v[236:239], v152 offset:38912
	ds_read_b128 v[240:243], v152 offset:39936
	global_load_lds_dwordx4 v[224:225], off
	v_lshl_add_u64 v[224:225], s[44:45], 0, v[134:135]
	s_mov_b32 m0, s49
	s_nop 0
	global_load_lds_dwordx4 v[224:225], off
	s_waitcnt vmcnt(8)
	s_waitcnt lgkmcnt(0)
	s_barrier
	s_setprio 1
	s_waitcnt lgkmcnt(0)
	v_mfma_f32_16x16x32_bf16 v[126:129], v[142:145], v[182:185], v[126:129]
	v_mfma_f32_16x16x32_bf16 v[122:125], v[158:161], v[182:185], v[122:125]
	v_mfma_f32_16x16x32_bf16 v[110:113], v[142:145], v[190:193], v[110:113]
	v_mfma_f32_16x16x32_bf16 v[106:109], v[158:161], v[190:193], v[106:109]
	v_mfma_f32_16x16x32_bf16 v[94:97], v[142:145], v[228:231], v[94:97]
	v_mfma_f32_16x16x32_bf16 v[90:93], v[158:161], v[228:231], v[90:93]
	v_mfma_f32_16x16x32_bf16 v[78:81], v[142:145], v[236:239], v[78:81]
	v_mfma_f32_16x16x32_bf16 v[74:77], v[158:161], v[236:239], v[74:77]
	v_mfma_f32_16x16x32_bf16 v[126:129], v[154:157], v[186:189], v[126:129]
	v_mfma_f32_16x16x32_bf16 v[122:125], v[162:165], v[186:189], v[122:125]
	v_mfma_f32_16x16x32_bf16 v[110:113], v[154:157], v[210:213], v[110:113]
	v_mfma_f32_16x16x32_bf16 v[106:109], v[162:165], v[210:213], v[106:109]
	v_mfma_f32_16x16x32_bf16 v[94:97], v[154:157], v[232:235], v[94:97]
	v_mfma_f32_16x16x32_bf16 v[90:93], v[162:165], v[232:235], v[90:93]
	v_mfma_f32_16x16x32_bf16 v[78:81], v[154:157], v[240:243], v[78:81]
	v_mfma_f32_16x16x32_bf16 v[74:77], v[162:165], v[240:243], v[74:77]
	s_setprio 0
	s_cmp_eq_u32 s53, 18
	s_cbranch_scc1 .Linp_skip_2
	s_setprio 1
	v_mfma_f32_16x16x32_bf16 v[118:121], v[166:169], v[182:185], v[118:121]
	v_mfma_f32_16x16x32_bf16 v[114:117], v[174:177], v[182:185], v[114:117]
	v_mfma_f32_16x16x32_bf16 v[102:105], v[166:169], v[190:193], v[102:105]
	v_mfma_f32_16x16x32_bf16 v[98:101], v[174:177], v[190:193], v[98:101]
	v_mfma_f32_16x16x32_bf16 v[86:89], v[166:169], v[228:231], v[86:89]
	v_mfma_f32_16x16x32_bf16 v[82:85], v[174:177], v[228:231], v[82:85]
	v_mfma_f32_16x16x32_bf16 v[70:73], v[166:169], v[236:239], v[70:73]
	v_mfma_f32_16x16x32_bf16 v[66:69], v[174:177], v[236:239], v[66:69]
	v_mfma_f32_16x16x32_bf16 v[118:121], v[170:173], v[186:189], v[118:121]
	v_mfma_f32_16x16x32_bf16 v[114:117], v[178:181], v[186:189], v[114:117]
	v_mfma_f32_16x16x32_bf16 v[102:105], v[170:173], v[210:213], v[102:105]
	v_mfma_f32_16x16x32_bf16 v[98:101], v[178:181], v[210:213], v[98:101]
	v_mfma_f32_16x16x32_bf16 v[86:89], v[170:173], v[232:235], v[86:89]
	v_mfma_f32_16x16x32_bf16 v[82:85], v[178:181], v[232:235], v[82:85]
	v_mfma_f32_16x16x32_bf16 v[70:73], v[170:173], v[240:243], v[70:73]
	v_mfma_f32_16x16x32_bf16 v[66:69], v[178:181], v[240:243], v[66:69]
	s_setprio 0
; #define PG8_STAGE(bufoff, gbase, voff) do { _Pragma("unroll") for (int _i = 0; _i < 2; ++_i) \
;         __builtin_amdgcn_global_load_lds((const unsigned*)((const char*)(gbase) + (voff)[_i]), (PG8_LAS unsigned*)(lds + (bufoff) + ldsw + _i * 8192), 16, 0, 0); } while (0)
; #define PG8_LDA(dst, b, h) do { _Pragma("unroll") for (int m = 0; m < 4; ++m) _Pragma("unroll") for (int k = 0; k < 2; ++k) dst[m][k] = *(const PG8_LAS bf16x8*)(lds + PG8_SA(b, h) + aoff + m * 2048 + k * 1024); } while (0)
; #define PG8_MMA(ai, bj, At, Bt) do { __builtin_amdgcn_s_setprio(1); _Pragma("unroll") for (int m = 0; m < 4; ++m) _Pragma("unroll") for (int n = 0; n < 2; ++n) _Pragma("unroll") for (int k = 0; k < 2; ++k) \
;         acc[ai][bj][m][n] = __builtin_amdgcn_mfma_f32_16x16x32_bf16(Bt[n][k], At[m][k], acc[ai][bj][m][n], 0, 0, 0); __builtin_amdgcn_s_setprio(0); } while (0)
; #define PG8_WAIT_V(n) asm volatile("s_waitcnt vmcnt(" #n ")" ::: "memory")
; #define PG8_WAIT_L(n) asm volatile("s_waitcnt lgkmcnt(" #n ")" ::: "memory")
; #define PG8_BAR __builtin_amdgcn_s_barrier()
; #define PG8_SCHED __builtin_amdgcn_sched_barrier(0)
; template <class Epi, class Sched, bool ALIGN_EPI = false, bool SP2 = false>
; __device__ __forceinline__ void gemm_phase(PG8_LAS unsigned char* lds, const Gemm g, const Sched& S, const Epi& E) {
;     ...
;             PG8_WAIT_V(8); PG8_WAIT_L(0); PG8_BAR; PG8_MMA(0, 0, At, B0); PG8_MMA(0, 1, At, B1); PG8_BAR; PG8_SCHED;
;             PG8_LDA(At, 1, 1); PG8_STAGE(PG8_SB(1, 0), b3, voffB); PG8_STAGE(PG8_SB(1, 1), b3 + hstepB, voffB); PG8_STAGE(PG8_SA(1, 0), a3, voffA);
;             PG8_WAIT_V(8); PG8_WAIT_L(0); PG8_BAR; PG8_MMA(1, 0, At, B0); PG8_MMA(1, 1, At, B1); PG8_BAR; PG8_SCHED;
.Linp_skip_2:
	s_barrier
	s_add_i32 s2, s2, s36
	v_lshl_add_u64 v[146:147], v[146:147], 0, s[94:95]
	s_mov_b32 m0, s2
	ds_read_b128 v[182:185], v152 offset:49152
	ds_read_b128 v[186:189], v152 offset:50176
	ds_read_b128 v[190:193], v152 offset:51200
	ds_read_b128 v[210:213], v152 offset:52224
	ds_read_b128 v[228:231], v152 offset:53248
	ds_read_b128 v[232:235], v152 offset:54272
	ds_read_b128 v[236:239], v152 offset:55296
	ds_read_b128 v[240:243], v152 offset:56320
	global_load_lds_dwordx4 v[146:147], off
	s_add_i32 m0, s2, 0x2000
	s_add_u32 s42, s42, 0x80080
	v_lshl_add_u64 v[146:147], v[194:195], 0, s[94:95]
	s_addc_u32 s43, s43, 0
	s_add_i32 s2, s33, s36
	global_load_lds_dwordx4 v[146:147], off
	v_lshl_add_u64 v[146:147], s[42:43], 0, v[0:1]
	s_mov_b32 m0, s2
	s_nop 0
	global_load_lds_dwordx4 v[146:147], off
	v_lshl_add_u64 v[146:147], s[42:43], 0, v[132:133]
	s_add_i32 m0, s2, 0x2000
	s_nop 0
	global_load_lds_dwordx4 v[146:147], off
	v_lshl_add_u64 v[146:147], v[214:215], 0, s[94:95]
	s_mov_b32 m0, s50
	s_nop 0
	global_load_lds_dwordx4 v[146:147], off
	v_lshl_add_u64 v[146:147], v[222:223], 0, s[94:95]
	s_mov_b32 m0, s51
	s_nop 0
	global_load_lds_dwordx4 v[146:147], off
	s_waitcnt vmcnt(8)
	s_waitcnt lgkmcnt(0)
	s_barrier
	s_setprio 1
	s_waitcnt lgkmcnt(0)
	v_mfma_f32_16x16x32_bf16 v[62:65], v[142:145], v[182:185], v[62:65]
	v_mfma_f32_16x16x32_bf16 v[58:61], v[158:161], v[182:185], v[58:61]
	v_mfma_f32_16x16x32_bf16 v[46:49], v[142:145], v[190:193], v[46:49]
	v_mfma_f32_16x16x32_bf16 v[42:45], v[158:161], v[190:193], v[42:45]
	v_mfma_f32_16x16x32_bf16 v[30:33], v[142:145], v[228:231], v[30:33]
	v_mfma_f32_16x16x32_bf16 v[26:29], v[158:161], v[228:231], v[26:29]
	v_mfma_f32_16x16x32_bf16 v[14:17], v[142:145], v[236:239], v[14:17]
	v_mfma_f32_16x16x32_bf16 v[10:13], v[158:161], v[236:239], v[10:13]
	v_mfma_f32_16x16x32_bf16 v[62:65], v[154:157], v[186:189], v[62:65]
	v_mfma_f32_16x16x32_bf16 v[58:61], v[162:165], v[186:189], v[58:61]
	v_mfma_f32_16x16x32_bf16 v[46:49], v[154:157], v[210:213], v[46:49]
	v_mfma_f32_16x16x32_bf16 v[42:45], v[162:165], v[210:213], v[42:45]
	v_mfma_f32_16x16x32_bf16 v[30:33], v[154:157], v[232:235], v[30:33]
	v_mfma_f32_16x16x32_bf16 v[26:29], v[162:165], v[232:235], v[26:29]
	v_mfma_f32_16x16x32_bf16 v[14:17], v[154:157], v[240:243], v[14:17]
	v_mfma_f32_16x16x32_bf16 v[10:13], v[162:165], v[240:243], v[10:13]
	s_setprio 0
	s_cmp_eq_u32 s53, 18
	s_cbranch_scc1 .Linp_skip_3
	s_setprio 1
	v_mfma_f32_16x16x32_bf16 v[54:57], v[166:169], v[182:185], v[54:57]
	v_mfma_f32_16x16x32_bf16 v[50:53], v[174:177], v[182:185], v[50:53]
	v_mfma_f32_16x16x32_bf16 v[38:41], v[166:169], v[190:193], v[38:41]
	v_mfma_f32_16x16x32_bf16 v[34:37], v[174:177], v[190:193], v[34:37]
	v_mfma_f32_16x16x32_bf16 v[22:25], v[166:169], v[228:231], v[22:25]
	v_mfma_f32_16x16x32_bf16 v[18:21], v[174:177], v[228:231], v[18:21]
	v_mfma_f32_16x16x32_bf16 v[6:9], v[166:169], v[236:239], v[6:9]
	v_mfma_f32_16x16x32_bf16 v[2:5], v[174:177], v[236:239], v[2:5]
	v_mfma_f32_16x16x32_bf16 v[54:57], v[170:173], v[186:189], v[54:57]
	v_mfma_f32_16x16x32_bf16 v[50:53], v[178:181], v[186:189], v[50:53]
	v_mfma_f32_16x16x32_bf16 v[38:41], v[170:173], v[210:213], v[38:41]
	v_mfma_f32_16x16x32_bf16 v[34:37], v[178:181], v[210:213], v[34:37]
	v_mfma_f32_16x16x32_bf16 v[22:25], v[170:173], v[232:235], v[22:25]
	v_mfma_f32_16x16x32_bf16 v[18:21], v[178:181], v[232:235], v[18:21]
	v_mfma_f32_16x16x32_bf16 v[6:9], v[170:173], v[240:243], v[6:9]
	v_mfma_f32_16x16x32_bf16 v[2:5], v[178:181], v[240:243], v[2:5]
	s_setprio 0
.Linp_skip_3:
	s_barrier
	s_add_i32 s62, s62, 2
	s_add_u32 s6, s6, 0x100
	s_addc_u32 s7, s7, 0
	s_add_u32 s60, s60, 0x100
	s_addc_u32 s61, s61, 0
	s_cmp_gt_u32 s62, 29
	s_cbranch_scc0 .LBB0_1434
	s_and_b64 vcc, exec, s[12:13]
	s_cbranch_vccz .LBB0_1437
	s_barrier
